# k23 + asymmetric static priority in the diff-attention key loop (workgroups below 256 raised), reset at loop exit
# baseline (speedup 1.0000x reference)
.LBB0_1040:
	v_readlane_b32 s15, v253, 0
	s_cmpk_lt_u32 s15, 0x100
	s_cbranch_scc0 .Lap_skip
	s_setprio 2

.LBB0_1044:
	s_setprio 0
	v_lshl_add_u32 v113, v214, 1, v215
	s_waitcnt vmcnt(7)
	ds_read_b128 v[16:19], v113 offset:41472
	s_waitcnt vmcnt(6)
	ds_read_b128 v[20:23], v113 offset:36992
	s_waitcnt vmcnt(5)
	ds_read_b128 v[32:35], v113 offset:36864
	s_waitcnt vmcnt(4)
	v_xor_b32_e32 v44, 0x80000000, v213
	v_mov_b32_e32 v45, v44
	v_mov_b32_e32 v46, v44
	v_mov_b32_e32 v47, v44
	s_waitcnt vmcnt(0)
	v_xor_b32_e32 v48, 0x80000000, v212
	v_mov_b32_e32 v49, v48
	v_mov_b32_e32 v50, v48
	v_mov_b32_e32 v51, v48
	s_waitcnt lgkmcnt(0)
	v_mfma_f32_16x16x32_bf16 v[32:35], v[32:35], v[12:15], v[44:47]
	ds_read_b128 v[52:55], v113 offset:41600
	v_mfma_f32_16x16x32_bf16 v[20:23], v[20:23], v[8:11], v[48:51]
	ds_read_b128 v[56:59], v113 offset:46080
	v_mfma_f32_16x16x32_bf16 v[60:63], v[16:19], v[12:15], v[44:47]
	ds_read_b128 v[16:19], v113 offset:46208
	s_waitcnt lgkmcnt(2)
	v_mfma_f32_16x16x32_bf16 v[52:55], v[52:55], v[8:11], v[48:51]
	ds_read_b128 v[114:117], v113 offset:50688
	s_waitcnt lgkmcnt(2)
	v_mfma_f32_16x16x32_bf16 v[56:59], v[56:59], v[12:15], v[44:47]
	ds_read_b128 v[118:121], v113 offset:50816
	s_waitcnt lgkmcnt(2)
	v_mfma_f32_16x16x32_bf16 v[122:125], v[16:19], v[8:11], v[48:51]
	ds_read_b128 v[16:19], v113 offset:36928
	s_waitcnt lgkmcnt(2)
	v_mfma_f32_16x16x32_bf16 v[114:117], v[114:117], v[12:15], v[44:47]
	ds_read_b128 v[12:15], v113 offset:37056
	s_waitcnt lgkmcnt(2)
	v_mfma_f32_16x16x32_bf16 v[48:51], v[118:121], v[8:11], v[48:51]
	ds_read_b128 v[8:11], v113 offset:41536
	s_waitcnt lgkmcnt(2)
	v_mfma_f32_16x16x32_bf16 v[44:47], v[16:19], v[4:7], v[32:35]
	ds_read_b128 v[118:121], v113 offset:41664
	s_waitcnt lgkmcnt(2)
	v_mfma_f32_16x16x32_bf16 v[16:19], v[12:15], v[0:3], v[20:23]
	s_nop 2
	ds_read_b128 v[20:23], v113 offset:46144
	s_waitcnt lgkmcnt(2)
	v_mfma_f32_16x16x32_bf16 v[32:35], v[8:11], v[4:7], v[60:63]
	ds_read_b128 v[8:11], v113 offset:46272
	s_waitcnt lgkmcnt(2)
	v_mfma_f32_16x16x32_bf16 v[12:15], v[118:121], v[0:3], v[52:55]
	s_nop 2
	ds_read_b128 v[52:55], v113 offset:50752
	s_waitcnt lgkmcnt(2)
	v_mfma_f32_16x16x32_bf16 v[20:23], v[20:23], v[4:7], v[56:59]
	s_nop 2
	ds_read_b128 v[56:59], v113 offset:50880
	s_waitcnt lgkmcnt(2)
	v_mfma_f32_16x16x32_bf16 v[8:11], v[8:11], v[0:3], v[122:125]
	s_waitcnt lgkmcnt(1)
	v_mfma_f32_16x16x32_bf16 v[4:7], v[52:55], v[4:7], v[114:117]
	s_waitcnt lgkmcnt(0)
	v_mfma_f32_16x16x32_bf16 v[0:3], v[56:59], v[0:3], v[48:51]
	s_nop 2
	v_max_f32_e32 v48, v45, v45
	v_max_f32_e32 v49, v44, v44
	v_max_f32_e32 v48, v49, v48
	v_max3_f32 v48, v48, v46, v47
	v_max3_f32 v48, v48, v32, v33
	v_max3_f32 v48, v48, v34, v35
	v_max3_f32 v48, v48, v20, v21
	v_max3_f32 v48, v48, v22, v23
	v_max3_f32 v48, v48, v4, v5
	v_max3_f32 v48, v48, v6, v7
	ds_bpermute_b32 v49, v145, v48
	s_waitcnt lgkmcnt(0)
	v_max_f32_e32 v49, v49, v49
	v_max_f32_e32 v48, v48, v49
	ds_bpermute_b32 v49, v147, v48
	s_waitcnt lgkmcnt(0)
	v_max_f32_e32 v49, v49, v49
	v_max_f32_e32 v48, v48, v49
	v_cmp_lt_f32_e32 vcc, s79, v48
	s_cbranch_vccz .LBB0_1046
	s_nop 0
	v_cndmask_b32_e32 v49, 0, v48, vcc
	v_exp_f32_e64 v48, -v49
	v_sub_f32_e32 v44, v44, v49
	v_sub_f32_e32 v45, v45, v49
	v_sub_f32_e32 v46, v46, v49
	v_pk_mul_f32 v[30:31], v[30:31], v[48:49] op_sel_hi:[1,0]
	v_pk_mul_f32 v[28:29], v[28:29], v[48:49] op_sel_hi:[1,0]
	v_pk_mul_f32 v[42:43], v[42:43], v[48:49] op_sel_hi:[1,0]
	v_pk_mul_f32 v[40:41], v[40:41], v[48:49] op_sel_hi:[1,0]
	v_pk_mul_f32 v[70:71], v[70:71], v[48:49] op_sel_hi:[1,0]
	v_pk_mul_f32 v[68:69], v[68:69], v[48:49] op_sel_hi:[1,0]
	v_pk_mul_f32 v[78:79], v[78:79], v[48:49] op_sel_hi:[1,0]
	v_pk_mul_f32 v[76:77], v[76:77], v[48:49] op_sel_hi:[1,0]
	v_pk_mul_f32 v[86:87], v[86:87], v[48:49] op_sel_hi:[1,0]
	v_pk_mul_f32 v[84:85], v[84:85], v[48:49] op_sel_hi:[1,0]
	v_pk_mul_f32 v[94:95], v[94:95], v[48:49] op_sel_hi:[1,0]
	v_pk_mul_f32 v[92:93], v[92:93], v[48:49] op_sel_hi:[1,0]
	v_pk_mul_f32 v[102:103], v[102:103], v[48:49] op_sel_hi:[1,0]
	v_pk_mul_f32 v[100:101], v[100:101], v[48:49] op_sel_hi:[1,0]
	v_pk_mul_f32 v[110:111], v[110:111], v[48:49] op_sel_hi:[1,0]
	v_pk_mul_f32 v[108:109], v[108:109], v[48:49] op_sel_hi:[1,0]
	v_mul_f32_e32 v171, v171, v48
	v_sub_f32_e32 v47, v47, v49
	v_sub_f32_e32 v32, v32, v49
	v_sub_f32_e32 v33, v33, v49
	v_sub_f32_e32 v34, v34, v49
	v_sub_f32_e32 v35, v35, v49
	v_sub_f32_e32 v20, v20, v49
	v_sub_f32_e32 v21, v21, v49
	v_sub_f32_e32 v22, v22, v49
	v_sub_f32_e32 v23, v23, v49
	v_sub_f32_e32 v4, v4, v49
	v_sub_f32_e32 v5, v5, v49
	v_sub_f32_e32 v6, v6, v49
	v_sub_f32_e32 v7, v7, v49
